# hand-written grid barrier, TOP with return + TOPGEN polling (no XGEN atomic, no division)
# speedup vs baseline: 1.0020x; 1.0020x over previous
.LBB0_146:
	s_or_b64 exec, exec, s[4:5]
	s_cmp_lt_u32 s61, 2
	s_cbranch_scc1 .LBB0_200
	s_waitcnt vmcnt(0) lgkmcnt(0)
	s_barrier
	v_readfirstlane_b32 s2, v162
	s_lshl_b32 s3, s33, 8
	s_add_u32 s6, s84, s3
	s_addc_u32 s7, s85, 0
	s_cmp_lg_u32 s2, 0
	s_cbranch_scc1 .Lgb1_wait
	s_mov_b64 s[8:9], exec
	s_mov_b64 exec, 1
	v_mov_b32_e32 v0, 0x12000
	ds_read_b64 v[2:3], v0
	v_mov_b32_e32 v0, 0x1400
	v_mov_b32_e32 v1, 1
	global_atomic_add v4, v0, v1, s[6:7] sc0
	s_mov_b32 s13, 0
	s_waitcnt lgkmcnt(0)
	v_readfirstlane_b32 s10, v2
	v_readfirstlane_b32 s11, v3
	v_mov_b32_e32 v0, 0x3400
	s_nop 3
	s_mul_i32 s10, s10, 2
	s_mul_i32 s11, s11, 2
	s_waitcnt vmcnt(0)
	v_readfirstlane_b32 s12, v4
	s_nop 3
	s_add_u32 s12, s12, 1
	s_cmp_lg_u32 s12, s10
	s_cbranch_scc1 .Lgb1_poll
	buffer_wbl2 sc1
	s_waitcnt vmcnt(0)
	global_atomic_add v4, v0, v1, s[84:85] sc0
	v_mov_b32_e32 v0, 0x3500
	s_waitcnt vmcnt(0)
	v_readfirstlane_b32 s12, v4
	s_nop 3
	s_add_u32 s12, s12, 1
	s_cmp_lg_u32 s12, s11
	s_cbranch_scc1 .Lgb1_poll
	global_atomic_add v0, v1, s[84:85]
.Lgb1_poll:
	v_mov_b32_e32 v0, 0x3500
.Lgb1_loop:
	global_load_dword v4, v0, s[84:85] sc1
	s_add_u32 s13, s13, 1
	s_waitcnt vmcnt(0)
	v_readfirstlane_b32 s12, v4
	s_nop 3
	s_cmp_gt_u32 s13, 0x80000
	s_cbranch_scc1 .Lgb1_done
	s_cmp_ge_u32 s12, 2
	s_cbranch_scc1 .Lgb1_done
	s_sleep 1
	s_branch .Lgb1_loop

.LBB0_418:
	s_cmp_lt_i32 s61, 3
	s_cbranch_scc1 .LBB0_472
	s_waitcnt vmcnt(0) lgkmcnt(0)
	s_barrier
	v_readfirstlane_b32 s2, v162
	s_lshl_b32 s3, s33, 8
	s_add_u32 s6, s84, s3
	s_addc_u32 s7, s85, 0
	s_cmp_lg_u32 s2, 0
	s_cbranch_scc1 .Lgb2_wait
	s_mov_b64 s[8:9], exec
	s_mov_b64 exec, 1
	v_mov_b32_e32 v0, 0x12000
	ds_read_b64 v[2:3], v0
	v_mov_b32_e32 v0, 0x1400
	v_mov_b32_e32 v1, 1
	global_atomic_add v4, v0, v1, s[6:7] sc0
	s_mov_b32 s13, 0
	s_waitcnt lgkmcnt(0)
	v_readfirstlane_b32 s10, v2
	v_readfirstlane_b32 s11, v3
	v_mov_b32_e32 v0, 0x3400
	s_nop 3
	s_mul_i32 s10, s10, 3
	s_mul_i32 s11, s11, 3
	s_waitcnt vmcnt(0)
	v_readfirstlane_b32 s12, v4
	s_nop 3
	s_add_u32 s12, s12, 1
	s_cmp_lg_u32 s12, s10
	s_cbranch_scc1 .Lgb2_poll
	buffer_wbl2 sc1
	s_waitcnt vmcnt(0)
	global_atomic_add v4, v0, v1, s[84:85] sc0
	v_mov_b32_e32 v0, 0x3500
	s_waitcnt vmcnt(0)
	v_readfirstlane_b32 s12, v4
	s_nop 3
	s_add_u32 s12, s12, 1
	s_cmp_lg_u32 s12, s11
	s_cbranch_scc1 .Lgb2_poll
	global_atomic_add v0, v1, s[84:85]

.Lgb2_loop:
	global_load_dword v4, v0, s[84:85] sc1
	s_add_u32 s13, s13, 1
	s_waitcnt vmcnt(0)
	v_readfirstlane_b32 s12, v4
	s_nop 3
	s_cmp_gt_u32 s13, 0x80000
	s_cbranch_scc1 .Lgb2_done
	s_cmp_ge_u32 s12, 3
	s_cbranch_scc1 .Lgb2_done
	s_sleep 1
	s_branch .Lgb2_loop

.LBB0_491:
	s_or_b64 exec, exec, s[4:5]
	s_cmp_lt_i32 s61, 4
	s_cbranch_scc1 .LBB0_545
	s_waitcnt vmcnt(0) lgkmcnt(0)
	s_barrier
	v_readfirstlane_b32 s2, v162
	s_lshl_b32 s3, s33, 8
	s_add_u32 s6, s84, s3
	s_addc_u32 s7, s85, 0
	s_cmp_lg_u32 s2, 0
	s_cbranch_scc1 .Lgb3_wait
	s_mov_b64 s[8:9], exec
	s_mov_b64 exec, 1
	v_mov_b32_e32 v0, 0x12000
	ds_read_b64 v[2:3], v0
	v_mov_b32_e32 v0, 0x1400
	v_mov_b32_e32 v1, 1
	global_atomic_add v4, v0, v1, s[6:7] sc0
	s_mov_b32 s13, 0
	s_waitcnt lgkmcnt(0)
	v_readfirstlane_b32 s10, v2
	v_readfirstlane_b32 s11, v3
	v_mov_b32_e32 v0, 0x3400
	s_nop 3
	s_mul_i32 s10, s10, 4
	s_mul_i32 s11, s11, 4
	s_waitcnt vmcnt(0)
	v_readfirstlane_b32 s12, v4
	s_nop 3
	s_add_u32 s12, s12, 1
	s_cmp_lg_u32 s12, s10
	s_cbranch_scc1 .Lgb3_poll
	buffer_wbl2 sc1
	s_waitcnt vmcnt(0)
	global_atomic_add v4, v0, v1, s[84:85] sc0
	v_mov_b32_e32 v0, 0x3500
	s_waitcnt vmcnt(0)
	v_readfirstlane_b32 s12, v4
	s_nop 3
	s_add_u32 s12, s12, 1
	s_cmp_lg_u32 s12, s11
	s_cbranch_scc1 .Lgb3_poll
	global_atomic_add v0, v1, s[84:85]

.Lgb3_loop:
	global_load_dword v4, v0, s[84:85] sc1
	s_add_u32 s13, s13, 1
	s_waitcnt vmcnt(0)
	v_readfirstlane_b32 s12, v4
	s_nop 3
	s_cmp_gt_u32 s13, 0x80000
	s_cbranch_scc1 .Lgb3_done
	s_cmp_ge_u32 s12, 4
	s_cbranch_scc1 .Lgb3_done
	s_sleep 1
	s_branch .Lgb3_loop

.LBB0_721:
	s_cmp_lt_i32 s61, 5
	s_cbranch_scc1 .LBB0_775
	s_waitcnt vmcnt(0) lgkmcnt(0)
	s_barrier
	v_readfirstlane_b32 s2, v162
	s_lshl_b32 s3, s33, 8
	s_add_u32 s6, s84, s3
	s_addc_u32 s7, s85, 0
	s_cmp_lg_u32 s2, 0
	s_cbranch_scc1 .Lgb4_wait
	s_mov_b64 s[8:9], exec
	s_mov_b64 exec, 1
	v_mov_b32_e32 v0, 0x12000
	ds_read_b64 v[2:3], v0
	v_mov_b32_e32 v0, 0x1400
	v_mov_b32_e32 v1, 1
	global_atomic_add v4, v0, v1, s[6:7] sc0
	s_mov_b32 s13, 0
	s_waitcnt lgkmcnt(0)
	v_readfirstlane_b32 s10, v2
	v_readfirstlane_b32 s11, v3
	v_mov_b32_e32 v0, 0x3400
	s_nop 3
	s_mul_i32 s10, s10, 5
	s_mul_i32 s11, s11, 5
	s_waitcnt vmcnt(0)
	v_readfirstlane_b32 s12, v4
	s_nop 3
	s_add_u32 s12, s12, 1
	s_cmp_lg_u32 s12, s10
	s_cbranch_scc1 .Lgb4_poll
	buffer_wbl2 sc1
	s_waitcnt vmcnt(0)
	global_atomic_add v4, v0, v1, s[84:85] sc0
	v_mov_b32_e32 v0, 0x3500
	s_waitcnt vmcnt(0)
	v_readfirstlane_b32 s12, v4
	s_nop 3
	s_add_u32 s12, s12, 1
	s_cmp_lg_u32 s12, s11
	s_cbranch_scc1 .Lgb4_poll
	global_atomic_add v0, v1, s[84:85]

.Lgb4_loop:
	global_load_dword v4, v0, s[84:85] sc1
	s_add_u32 s13, s13, 1
	s_waitcnt vmcnt(0)
	v_readfirstlane_b32 s12, v4
	s_nop 3
	s_cmp_gt_u32 s13, 0x80000
	s_cbranch_scc1 .Lgb4_done
	s_cmp_ge_u32 s12, 5
	s_cbranch_scc1 .Lgb4_done
	s_sleep 1
	s_branch .Lgb4_loop

.LBB0_779:
	s_or_b64 exec, exec, s[8:9]
	s_cmp_lt_u32 s61, 6
	s_cbranch_scc1 .LBB0_833
	s_waitcnt vmcnt(0) lgkmcnt(0)
	s_barrier
	v_readfirstlane_b32 s2, v162
	s_lshl_b32 s3, s33, 8
	s_add_u32 s6, s84, s3
	s_addc_u32 s7, s85, 0
	s_cmp_lg_u32 s2, 0
	s_cbranch_scc1 .Lgb5_wait
	s_mov_b64 s[8:9], exec
	s_mov_b64 exec, 1
	v_mov_b32_e32 v0, 0x12000
	ds_read_b64 v[2:3], v0
	v_mov_b32_e32 v0, 0x1400
	v_mov_b32_e32 v1, 1
	global_atomic_add v4, v0, v1, s[6:7] sc0
	s_mov_b32 s13, 0
	s_waitcnt lgkmcnt(0)
	v_readfirstlane_b32 s10, v2
	v_readfirstlane_b32 s11, v3
	v_mov_b32_e32 v0, 0x3400
	s_nop 3
	s_mul_i32 s10, s10, 6
	s_mul_i32 s11, s11, 6
	s_waitcnt vmcnt(0)
	v_readfirstlane_b32 s12, v4
	s_nop 3
	s_add_u32 s12, s12, 1
	s_cmp_lg_u32 s12, s10
	s_cbranch_scc1 .Lgb5_poll
	buffer_wbl2 sc1
	s_waitcnt vmcnt(0)
	global_atomic_add v4, v0, v1, s[84:85] sc0
	v_mov_b32_e32 v0, 0x3500
	s_waitcnt vmcnt(0)
	v_readfirstlane_b32 s12, v4
	s_nop 3
	s_add_u32 s12, s12, 1
	s_cmp_lg_u32 s12, s11
	s_cbranch_scc1 .Lgb5_poll
	global_atomic_add v0, v1, s[84:85]

.Lgb5_loop:
	global_load_dword v4, v0, s[84:85] sc1
	s_add_u32 s13, s13, 1
	s_waitcnt vmcnt(0)
	v_readfirstlane_b32 s12, v4
	s_nop 3
	s_cmp_gt_u32 s13, 0x80000
	s_cbranch_scc1 .Lgb5_done
	s_cmp_ge_u32 s12, 6
	s_cbranch_scc1 .Lgb5_done
	s_sleep 1
	s_branch .Lgb5_loop

.LBB0_897:
	s_or_b64 exec, exec, s[10:11]
	s_cmp_lt_u32 s61, 8
	s_cbranch_scc1 .LBB0_951
	s_waitcnt vmcnt(0) lgkmcnt(0)
	s_barrier
	v_readfirstlane_b32 s2, v162
	s_lshl_b32 s3, s33, 8
	s_add_u32 s6, s84, s3
	s_addc_u32 s7, s85, 0
	s_cmp_lg_u32 s2, 0
	s_cbranch_scc1 .Lgb7_wait
	s_mov_b64 s[8:9], exec
	s_mov_b64 exec, 1
	v_mov_b32_e32 v0, 0x12000
	ds_read_b64 v[2:3], v0
	v_mov_b32_e32 v0, 0x1400
	v_mov_b32_e32 v1, 1
	global_atomic_add v4, v0, v1, s[6:7] sc0
	s_mov_b32 s13, 0
	s_waitcnt lgkmcnt(0)
	v_readfirstlane_b32 s10, v2
	v_readfirstlane_b32 s11, v3
	v_mov_b32_e32 v0, 0x3400
	s_nop 3
	s_mul_i32 s10, s10, 7
	s_mul_i32 s11, s11, 7
	s_waitcnt vmcnt(0)
	v_readfirstlane_b32 s12, v4
	s_nop 3
	s_add_u32 s12, s12, 1
	s_cmp_lg_u32 s12, s10
	s_cbranch_scc1 .Lgb7_poll
	buffer_wbl2 sc1
	s_waitcnt vmcnt(0)
	global_atomic_add v4, v0, v1, s[84:85] sc0
	v_mov_b32_e32 v0, 0x3500
	s_waitcnt vmcnt(0)
	v_readfirstlane_b32 s12, v4
	s_nop 3
	s_add_u32 s12, s12, 1
	s_cmp_lg_u32 s12, s11
	s_cbranch_scc1 .Lgb7_poll
	global_atomic_add v0, v1, s[84:85]

.Lgb7_loop:
	global_load_dword v4, v0, s[84:85] sc1
	s_add_u32 s13, s13, 1
	s_waitcnt vmcnt(0)
	v_readfirstlane_b32 s12, v4
	s_nop 3
	s_cmp_gt_u32 s13, 0x80000
	s_cbranch_scc1 .Lgb7_done
	s_cmp_ge_u32 s12, 7
	s_cbranch_scc1 .Lgb7_done
	s_sleep 1
	s_branch .Lgb7_loop

.Lf8_end:
.LBB0_961:
	s_cmp_lt_i32 s61, 9
	s_cbranch_scc1 .LBB0_1015
	s_waitcnt vmcnt(0) lgkmcnt(0)
	s_barrier
	v_readfirstlane_b32 s2, v162
	s_lshl_b32 s3, s33, 8
	s_add_u32 s6, s84, s3
	s_addc_u32 s7, s85, 0
	s_cmp_lg_u32 s2, 0
	s_cbranch_scc1 .Lgb8_wait
	s_mov_b64 s[8:9], exec
	s_mov_b64 exec, 1
	v_mov_b32_e32 v0, 0x12000
	ds_read_b64 v[2:3], v0
	v_mov_b32_e32 v0, 0x1400
	v_mov_b32_e32 v1, 1
	global_atomic_add v4, v0, v1, s[6:7] sc0
	s_mov_b32 s13, 0
	s_waitcnt lgkmcnt(0)
	v_readfirstlane_b32 s10, v2
	v_readfirstlane_b32 s11, v3
	v_mov_b32_e32 v0, 0x3400
	s_nop 3
	s_mul_i32 s10, s10, 8
	s_mul_i32 s11, s11, 8
	s_waitcnt vmcnt(0)
	v_readfirstlane_b32 s12, v4
	s_nop 3
	s_add_u32 s12, s12, 1
	s_cmp_lg_u32 s12, s10
	s_cbranch_scc1 .Lgb8_poll
	buffer_wbl2 sc1
	s_waitcnt vmcnt(0)
	global_atomic_add v4, v0, v1, s[84:85] sc0
	v_mov_b32_e32 v0, 0x3500
	s_waitcnt vmcnt(0)
	v_readfirstlane_b32 s12, v4
	s_nop 3
	s_add_u32 s12, s12, 1
	s_cmp_lg_u32 s12, s11
	s_cbranch_scc1 .Lgb8_poll
	global_atomic_add v0, v1, s[84:85]

.Lgb8_loop:
	global_load_dword v4, v0, s[84:85] sc1
	s_add_u32 s13, s13, 1
	s_waitcnt vmcnt(0)
	v_readfirstlane_b32 s12, v4
	s_nop 3
	s_cmp_gt_u32 s13, 0x80000
	s_cbranch_scc1 .Lgb8_done
	s_cmp_ge_u32 s12, 8
	s_cbranch_scc1 .Lgb8_done
	s_sleep 1
	s_branch .Lgb8_loop

.LBB0_1079:
	s_or_b64 exec, exec, s[10:11]
	s_cmp_lt_u32 s61, 11
	s_cbranch_scc1 .LBB0_1133
	s_waitcnt vmcnt(0) lgkmcnt(0)
	s_barrier
	v_readfirstlane_b32 s2, v162
	s_lshl_b32 s3, s33, 8
	s_add_u32 s6, s84, s3
	s_addc_u32 s7, s85, 0
	s_cmp_lg_u32 s2, 0
	s_cbranch_scc1 .Lgb10_wait
	s_mov_b64 s[8:9], exec
	s_mov_b64 exec, 1
	v_mov_b32_e32 v0, 0x12000
	ds_read_b64 v[2:3], v0
	v_mov_b32_e32 v0, 0x1400
	v_mov_b32_e32 v1, 1
	global_atomic_add v4, v0, v1, s[6:7] sc0
	s_mov_b32 s13, 0
	s_waitcnt lgkmcnt(0)
	v_readfirstlane_b32 s10, v2
	v_readfirstlane_b32 s11, v3
	v_mov_b32_e32 v0, 0x3400
	s_nop 3
	s_mul_i32 s10, s10, 9
	s_mul_i32 s11, s11, 9
	s_waitcnt vmcnt(0)
	v_readfirstlane_b32 s12, v4
	s_nop 3
	s_add_u32 s12, s12, 1
	s_cmp_lg_u32 s12, s10
	s_cbranch_scc1 .Lgb10_poll
	buffer_wbl2 sc1
	s_waitcnt vmcnt(0)
	global_atomic_add v4, v0, v1, s[84:85] sc0
	v_mov_b32_e32 v0, 0x3500
	s_waitcnt vmcnt(0)
	v_readfirstlane_b32 s12, v4
	s_nop 3
	s_add_u32 s12, s12, 1
	s_cmp_lg_u32 s12, s11
	s_cbranch_scc1 .Lgb10_poll
	global_atomic_add v0, v1, s[84:85]

.Lgb10_loop:
	global_load_dword v4, v0, s[84:85] sc1
	s_add_u32 s13, s13, 1
	s_waitcnt vmcnt(0)
	v_readfirstlane_b32 s12, v4
	s_nop 3
	s_cmp_gt_u32 s13, 0x80000
	s_cbranch_scc1 .Lgb10_done
	s_cmp_ge_u32 s12, 9
	s_cbranch_scc1 .Lgb10_done
	s_sleep 1
	s_branch .Lgb10_loop

.LBB0_1142:
	s_cmp_lt_i32 s61, 12
	s_cbranch_scc1 .LBB0_1196
	s_waitcnt vmcnt(0) lgkmcnt(0)
	s_barrier
	v_readfirstlane_b32 s2, v162
	s_lshl_b32 s3, s33, 8
	s_add_u32 s6, s84, s3
	s_addc_u32 s7, s85, 0
	s_cmp_lg_u32 s2, 0
	s_cbranch_scc1 .Lgb11_wait
	s_mov_b64 s[8:9], exec
	s_mov_b64 exec, 1
	v_mov_b32_e32 v0, 0x12000
	ds_read_b64 v[2:3], v0
	v_mov_b32_e32 v0, 0x1400
	v_mov_b32_e32 v1, 1
	global_atomic_add v4, v0, v1, s[6:7] sc0
	s_mov_b32 s13, 0
	s_waitcnt lgkmcnt(0)
	v_readfirstlane_b32 s10, v2
	v_readfirstlane_b32 s11, v3
	v_mov_b32_e32 v0, 0x3400
	s_nop 3
	s_mul_i32 s10, s10, 10
	s_mul_i32 s11, s11, 10
	s_waitcnt vmcnt(0)
	v_readfirstlane_b32 s12, v4
	s_nop 3
	s_add_u32 s12, s12, 1
	s_cmp_lg_u32 s12, s10
	s_cbranch_scc1 .Lgb11_poll
	buffer_wbl2 sc1
	s_waitcnt vmcnt(0)
	global_atomic_add v4, v0, v1, s[84:85] sc0
	v_mov_b32_e32 v0, 0x3500
	s_waitcnt vmcnt(0)
	v_readfirstlane_b32 s12, v4
	s_nop 3
	s_add_u32 s12, s12, 1
	s_cmp_lg_u32 s12, s11
	s_cbranch_scc1 .Lgb11_poll
	global_atomic_add v0, v1, s[84:85]

.Lgb11_loop:
	global_load_dword v4, v0, s[84:85] sc1
	s_add_u32 s13, s13, 1
	s_waitcnt vmcnt(0)
	v_readfirstlane_b32 s12, v4
	s_nop 3
	s_cmp_gt_u32 s13, 0x80000
	s_cbranch_scc1 .Lgb11_done
	s_cmp_ge_u32 s12, 10
	s_cbranch_scc1 .Lgb11_done
	s_sleep 1
	s_branch .Lgb11_loop

.LBB0_1206:
	s_cmp_lt_i32 s61, 13
	s_cbranch_scc1 .LBB0_1260
	s_waitcnt vmcnt(0) lgkmcnt(0)
	s_barrier
	v_readfirstlane_b32 s2, v162
	s_lshl_b32 s3, s33, 8
	s_add_u32 s6, s84, s3
	s_addc_u32 s7, s85, 0
	s_cmp_lg_u32 s2, 0
	s_cbranch_scc1 .Lgb12_wait
	s_mov_b64 s[8:9], exec
	s_mov_b64 exec, 1
	v_mov_b32_e32 v0, 0x12000
	ds_read_b64 v[2:3], v0
	v_mov_b32_e32 v0, 0x1400
	v_mov_b32_e32 v1, 1
	global_atomic_add v4, v0, v1, s[6:7] sc0
	s_mov_b32 s13, 0
	s_waitcnt lgkmcnt(0)
	v_readfirstlane_b32 s10, v2
	v_readfirstlane_b32 s11, v3
	v_mov_b32_e32 v0, 0x3400
	s_nop 3
	s_mul_i32 s10, s10, 11
	s_mul_i32 s11, s11, 11
	s_waitcnt vmcnt(0)
	v_readfirstlane_b32 s12, v4
	s_nop 3
	s_add_u32 s12, s12, 1
	s_cmp_lg_u32 s12, s10
	s_cbranch_scc1 .Lgb12_poll
	buffer_wbl2 sc1
	s_waitcnt vmcnt(0)
	global_atomic_add v4, v0, v1, s[84:85] sc0
	v_mov_b32_e32 v0, 0x3500
	s_waitcnt vmcnt(0)
	v_readfirstlane_b32 s12, v4
	s_nop 3
	s_add_u32 s12, s12, 1
	s_cmp_lg_u32 s12, s11
	s_cbranch_scc1 .Lgb12_poll
	global_atomic_add v0, v1, s[84:85]

.Lgb12_loop:
	global_load_dword v4, v0, s[84:85] sc1
	s_add_u32 s13, s13, 1
	s_waitcnt vmcnt(0)
	v_readfirstlane_b32 s12, v4
	s_nop 3
	s_cmp_gt_u32 s13, 0x80000
	s_cbranch_scc1 .Lgb12_done
	s_cmp_ge_u32 s12, 11
	s_cbranch_scc1 .Lgb12_done
	s_sleep 1
	s_branch .Lgb12_loop

.LBB0_1332:
	s_or_b64 exec, exec, s[10:11]
	s_cmp_lt_u32 s61, 15
	s_cbranch_scc1 .LBB0_1386
	s_waitcnt vmcnt(0) lgkmcnt(0)
	s_barrier
	v_readfirstlane_b32 s2, v162
	s_lshl_b32 s3, s33, 8
	s_add_u32 s6, s84, s3
	s_addc_u32 s7, s85, 0
	s_cmp_lg_u32 s2, 0
	s_cbranch_scc1 .Lgb14_wait
	s_mov_b64 s[8:9], exec
	s_mov_b64 exec, 1
	v_mov_b32_e32 v0, 0x12000
	ds_read_b64 v[2:3], v0
	v_mov_b32_e32 v0, 0x1400
	v_mov_b32_e32 v1, 1
	global_atomic_add v4, v0, v1, s[6:7] sc0
	s_mov_b32 s13, 0
	s_waitcnt lgkmcnt(0)
	v_readfirstlane_b32 s10, v2
	v_readfirstlane_b32 s11, v3
	v_mov_b32_e32 v0, 0x3400
	s_nop 3
	s_mul_i32 s10, s10, 12
	s_mul_i32 s11, s11, 12
	s_waitcnt vmcnt(0)
	v_readfirstlane_b32 s12, v4
	s_nop 3
	s_add_u32 s12, s12, 1
	s_cmp_lg_u32 s12, s10
	s_cbranch_scc1 .Lgb14_poll
	buffer_wbl2 sc1
	s_waitcnt vmcnt(0)
	global_atomic_add v4, v0, v1, s[84:85] sc0
	v_mov_b32_e32 v0, 0x3500
	s_waitcnt vmcnt(0)
	v_readfirstlane_b32 s12, v4
	s_nop 3
	s_add_u32 s12, s12, 1
	s_cmp_lg_u32 s12, s11
	s_cbranch_scc1 .Lgb14_poll
	global_atomic_add v0, v1, s[84:85]

.Lgb14_loop:
	global_load_dword v4, v0, s[84:85] sc1
	s_add_u32 s13, s13, 1
	s_waitcnt vmcnt(0)
	v_readfirstlane_b32 s12, v4
	s_nop 3
	s_cmp_gt_u32 s13, 0x80000
	s_cbranch_scc1 .Lgb14_done
	s_cmp_ge_u32 s12, 12
	s_cbranch_scc1 .Lgb14_done
	s_sleep 1
	s_branch .Lgb14_loop

.Lf15_end:
.LBB0_1396:
	s_cmp_lt_i32 s61, 16
	s_cbranch_scc1 .LBB0_1450
	s_waitcnt vmcnt(0) lgkmcnt(0)
	s_barrier
	v_readfirstlane_b32 s2, v162
	s_lshl_b32 s3, s33, 8
	s_add_u32 s6, s84, s3
	s_addc_u32 s7, s85, 0
	s_cmp_lg_u32 s2, 0
	s_cbranch_scc1 .Lgb15_wait
	s_mov_b64 s[8:9], exec
	s_mov_b64 exec, 1
	v_mov_b32_e32 v0, 0x12000
	ds_read_b64 v[2:3], v0
	v_mov_b32_e32 v0, 0x1400
	v_mov_b32_e32 v1, 1
	global_atomic_add v4, v0, v1, s[6:7] sc0
	s_mov_b32 s13, 0
	s_waitcnt lgkmcnt(0)
	v_readfirstlane_b32 s10, v2
	v_readfirstlane_b32 s11, v3
	v_mov_b32_e32 v0, 0x3400
	s_nop 3
	s_mul_i32 s10, s10, 13
	s_mul_i32 s11, s11, 13
	s_waitcnt vmcnt(0)
	v_readfirstlane_b32 s12, v4
	s_nop 3
	s_add_u32 s12, s12, 1
	s_cmp_lg_u32 s12, s10
	s_cbranch_scc1 .Lgb15_poll
	buffer_wbl2 sc1
	s_waitcnt vmcnt(0)
	global_atomic_add v4, v0, v1, s[84:85] sc0
	v_mov_b32_e32 v0, 0x3500
	s_waitcnt vmcnt(0)
	v_readfirstlane_b32 s12, v4
	s_nop 3
	s_add_u32 s12, s12, 1
	s_cmp_lg_u32 s12, s11
	s_cbranch_scc1 .Lgb15_poll
	global_atomic_add v0, v1, s[84:85]

.Lgb15_loop:
	global_load_dword v4, v0, s[84:85] sc1
	s_add_u32 s13, s13, 1
	s_waitcnt vmcnt(0)
	v_readfirstlane_b32 s12, v4
	s_nop 3
	s_cmp_gt_u32 s13, 0x80000
	s_cbranch_scc1 .Lgb15_done
	s_cmp_ge_u32 s12, 13
	s_cbranch_scc1 .Lgb15_done
	s_sleep 1
	s_branch .Lgb15_loop

.LBB0_1519:
	s_or_b64 exec, exec, s[4:5]
	s_cmp_lt_u32 s61, 18
	s_cbranch_scc1 .LBB0_1573
	s_waitcnt vmcnt(0) lgkmcnt(0)
	s_barrier
	v_readfirstlane_b32 s2, v162
	s_lshl_b32 s3, s33, 8
	s_add_u32 s6, s84, s3
	s_addc_u32 s7, s85, 0
	s_cmp_lg_u32 s2, 0
	s_cbranch_scc1 .Lgb17_wait
	s_mov_b64 s[8:9], exec
	s_mov_b64 exec, 1
	v_mov_b32_e32 v0, 0x12000
	ds_read_b64 v[2:3], v0
	v_mov_b32_e32 v0, 0x1400
	v_mov_b32_e32 v1, 1
	global_atomic_add v4, v0, v1, s[6:7] sc0
	s_mov_b32 s13, 0
	s_waitcnt lgkmcnt(0)
	v_readfirstlane_b32 s10, v2
	v_readfirstlane_b32 s11, v3
	v_mov_b32_e32 v0, 0x3400
	s_nop 3
	s_mul_i32 s10, s10, 14
	s_mul_i32 s11, s11, 14
	s_waitcnt vmcnt(0)
	v_readfirstlane_b32 s12, v4
	s_nop 3
	s_add_u32 s12, s12, 1
	s_cmp_lg_u32 s12, s10
	s_cbranch_scc1 .Lgb17_poll
	buffer_wbl2 sc1
	s_waitcnt vmcnt(0)
	global_atomic_add v4, v0, v1, s[84:85] sc0
	v_mov_b32_e32 v0, 0x3500
	s_waitcnt vmcnt(0)
	v_readfirstlane_b32 s12, v4
	s_nop 3
	s_add_u32 s12, s12, 1
	s_cmp_lg_u32 s12, s11
	s_cbranch_scc1 .Lgb17_poll
	global_atomic_add v0, v1, s[84:85]

.Lgb17_loop:
	global_load_dword v4, v0, s[84:85] sc1
	s_add_u32 s13, s13, 1
	s_waitcnt vmcnt(0)
	v_readfirstlane_b32 s12, v4
	s_nop 3
	s_cmp_gt_u32 s13, 0x80000
	s_cbranch_scc1 .Lgb17_done
	s_cmp_ge_u32 s12, 14
	s_cbranch_scc1 .Lgb17_done
	s_sleep 1
	s_branch .Lgb17_loop

.LBB0_1791:
	s_cmp_lt_i32 s61, 19
	s_mov_b64 s[84:85], s[76:77]
	s_cbranch_scc1 .LBB0_1845
	s_waitcnt vmcnt(0) lgkmcnt(0)
	s_barrier
	v_readfirstlane_b32 s2, v162
	s_lshl_b32 s3, s33, 8
	s_add_u32 s6, s84, s3
	s_addc_u32 s7, s85, 0
	s_cmp_lg_u32 s2, 0
	s_cbranch_scc1 .Lgb18_wait
	s_mov_b64 s[8:9], exec
	s_mov_b64 exec, 1
	v_mov_b32_e32 v0, 0x12000
	ds_read_b64 v[2:3], v0
	v_mov_b32_e32 v0, 0x1400
	v_mov_b32_e32 v1, 1
	global_atomic_add v4, v0, v1, s[6:7] sc0
	s_mov_b32 s13, 0
	s_waitcnt lgkmcnt(0)
	v_readfirstlane_b32 s10, v2
	v_readfirstlane_b32 s11, v3
	v_mov_b32_e32 v0, 0x3400
	s_nop 3
	s_mul_i32 s10, s10, 15
	s_mul_i32 s11, s11, 15
	s_waitcnt vmcnt(0)
	v_readfirstlane_b32 s12, v4
	s_nop 3
	s_add_u32 s12, s12, 1
	s_cmp_lg_u32 s12, s10
	s_cbranch_scc1 .Lgb18_poll
	buffer_wbl2 sc1
	s_waitcnt vmcnt(0)
	global_atomic_add v4, v0, v1, s[84:85] sc0
	v_mov_b32_e32 v0, 0x3500
	s_waitcnt vmcnt(0)
	v_readfirstlane_b32 s12, v4
	s_nop 3
	s_add_u32 s12, s12, 1
	s_cmp_lg_u32 s12, s11
	s_cbranch_scc1 .Lgb18_poll
	global_atomic_add v0, v1, s[84:85]

.Lgb18_loop:
	global_load_dword v4, v0, s[84:85] sc1
	s_add_u32 s13, s13, 1
	s_waitcnt vmcnt(0)
	v_readfirstlane_b32 s12, v4
	s_nop 3
	s_cmp_gt_u32 s13, 0x80000
	s_cbranch_scc1 .Lgb18_done
	s_cmp_ge_u32 s12, 15
	s_cbranch_scc1 .Lgb18_done
	s_sleep 1
	s_branch .Lgb18_loop

.LBB0_1864:
	s_or_b64 exec, exec, s[4:5]
	s_cmp_lt_i32 s61, 20
	s_cbranch_scc1 .LBB0_1918
	s_waitcnt vmcnt(0) lgkmcnt(0)
	s_barrier
	v_readfirstlane_b32 s2, v162
	s_lshl_b32 s3, s33, 8
	s_add_u32 s6, s84, s3
	s_addc_u32 s7, s85, 0
	s_cmp_lg_u32 s2, 0
	s_cbranch_scc1 .Lgb19_wait
	s_mov_b64 s[8:9], exec
	s_mov_b64 exec, 1
	v_mov_b32_e32 v0, 0x12000
	ds_read_b64 v[2:3], v0
	v_mov_b32_e32 v0, 0x1400
	v_mov_b32_e32 v1, 1
	global_atomic_add v4, v0, v1, s[6:7] sc0
	s_mov_b32 s13, 0
	s_waitcnt lgkmcnt(0)
	v_readfirstlane_b32 s10, v2
	v_readfirstlane_b32 s11, v3
	v_mov_b32_e32 v0, 0x3400
	s_nop 3
	s_mul_i32 s10, s10, 16
	s_mul_i32 s11, s11, 16
	s_waitcnt vmcnt(0)
	v_readfirstlane_b32 s12, v4
	s_nop 3
	s_add_u32 s12, s12, 1
	s_cmp_lg_u32 s12, s10
	s_cbranch_scc1 .Lgb19_poll
	buffer_wbl2 sc1
	s_waitcnt vmcnt(0)
	global_atomic_add v4, v0, v1, s[84:85] sc0
	v_mov_b32_e32 v0, 0x3500
	s_waitcnt vmcnt(0)
	v_readfirstlane_b32 s12, v4
	s_nop 3
	s_add_u32 s12, s12, 1
	s_cmp_lg_u32 s12, s11
	s_cbranch_scc1 .Lgb19_poll
	global_atomic_add v0, v1, s[84:85]

.Lgb19_loop:
	global_load_dword v4, v0, s[84:85] sc1
	s_add_u32 s13, s13, 1
	s_waitcnt vmcnt(0)
	v_readfirstlane_b32 s12, v4
	s_nop 3
	s_cmp_gt_u32 s13, 0x80000
	s_cbranch_scc1 .Lgb19_done
	s_cmp_ge_u32 s12, 16
	s_cbranch_scc1 .Lgb19_done
	s_sleep 1
	s_branch .Lgb19_loop

.LBB0_2180:
	s_cmp_lt_i32 s61, 21
	s_cbranch_scc1 .LBB0_2234
	s_waitcnt vmcnt(0) lgkmcnt(0)
	s_barrier
	v_readfirstlane_b32 s2, v162
	s_lshl_b32 s3, s33, 8
	s_add_u32 s6, s84, s3
	s_addc_u32 s7, s85, 0
	s_cmp_lg_u32 s2, 0
	s_cbranch_scc1 .Lgb20_wait
	s_mov_b64 s[8:9], exec
	s_mov_b64 exec, 1
	v_mov_b32_e32 v0, 0x12000
	ds_read_b64 v[2:3], v0
	v_mov_b32_e32 v0, 0x1400
	v_mov_b32_e32 v1, 1
	global_atomic_add v4, v0, v1, s[6:7] sc0
	s_mov_b32 s13, 0
	s_waitcnt lgkmcnt(0)
	v_readfirstlane_b32 s10, v2
	v_readfirstlane_b32 s11, v3
	v_mov_b32_e32 v0, 0x3400
	s_nop 3
	s_mul_i32 s10, s10, 17
	s_mul_i32 s11, s11, 17
	s_waitcnt vmcnt(0)
	v_readfirstlane_b32 s12, v4
	s_nop 3
	s_add_u32 s12, s12, 1
	s_cmp_lg_u32 s12, s10
	s_cbranch_scc1 .Lgb20_poll
	buffer_wbl2 sc1
	s_waitcnt vmcnt(0)
	global_atomic_add v4, v0, v1, s[84:85] sc0
	v_mov_b32_e32 v0, 0x3500
	s_waitcnt vmcnt(0)
	v_readfirstlane_b32 s12, v4
	s_nop 3
	s_add_u32 s12, s12, 1
	s_cmp_lg_u32 s12, s11
	s_cbranch_scc1 .Lgb20_poll
	global_atomic_add v0, v1, s[84:85]

.Lgb20_loop:
	global_load_dword v4, v0, s[84:85] sc1
	s_add_u32 s13, s13, 1
	s_waitcnt vmcnt(0)
	v_readfirstlane_b32 s12, v4
	s_nop 3
	s_cmp_gt_u32 s13, 0x80000
	s_cbranch_scc1 .Lgb20_done
	s_cmp_ge_u32 s12, 17
	s_cbranch_scc1 .Lgb20_done
	s_sleep 1
	s_branch .Lgb20_loop

.LBB0_2238:
	s_or_b64 exec, exec, s[6:7]
	s_cmp_lt_u32 s61, 22
	s_cbranch_scc1 .LBB0_2292
	s_waitcnt vmcnt(0) lgkmcnt(0)
	s_barrier
	v_readfirstlane_b32 s2, v162
	s_lshl_b32 s3, s33, 8
	s_add_u32 s6, s84, s3
	s_addc_u32 s7, s85, 0
	s_cmp_lg_u32 s2, 0
	s_cbranch_scc1 .Lgb21_wait
	s_mov_b64 s[8:9], exec
	s_mov_b64 exec, 1
	v_mov_b32_e32 v0, 0x12000
	ds_read_b64 v[2:3], v0
	v_mov_b32_e32 v0, 0x1400
	v_mov_b32_e32 v1, 1
	global_atomic_add v4, v0, v1, s[6:7] sc0
	s_mov_b32 s13, 0
	s_waitcnt lgkmcnt(0)
	v_readfirstlane_b32 s10, v2
	v_readfirstlane_b32 s11, v3
	v_mov_b32_e32 v0, 0x3400
	s_nop 3
	s_mul_i32 s10, s10, 18
	s_mul_i32 s11, s11, 18
	s_waitcnt vmcnt(0)
	v_readfirstlane_b32 s12, v4
	s_nop 3
	s_add_u32 s12, s12, 1
	s_cmp_lg_u32 s12, s10
	s_cbranch_scc1 .Lgb21_poll
	buffer_wbl2 sc1
	s_waitcnt vmcnt(0)
	global_atomic_add v4, v0, v1, s[84:85] sc0
	v_mov_b32_e32 v0, 0x3500
	s_waitcnt vmcnt(0)
	v_readfirstlane_b32 s12, v4
	s_nop 3
	s_add_u32 s12, s12, 1
	s_cmp_lg_u32 s12, s11
	s_cbranch_scc1 .Lgb21_poll
	global_atomic_add v0, v1, s[84:85]

.Lgb21_loop:
	global_load_dword v4, v0, s[84:85] sc1
	s_add_u32 s13, s13, 1
	s_waitcnt vmcnt(0)
	v_readfirstlane_b32 s12, v4
	s_nop 3
	s_cmp_gt_u32 s13, 0x80000
	s_cbranch_scc1 .Lgb21_done
	s_cmp_ge_u32 s12, 18
	s_cbranch_scc1 .Lgb21_done
	s_sleep 1
	s_branch .Lgb21_loop

.LBB0_2356:
	s_or_b64 exec, exec, s[10:11]
	s_cmp_lt_u32 s61, 24
	s_cbranch_scc1 .LBB0_2410
	s_waitcnt vmcnt(0) lgkmcnt(0)
	s_barrier
	v_readfirstlane_b32 s2, v162
	s_lshl_b32 s3, s33, 8
	s_add_u32 s6, s84, s3
	s_addc_u32 s7, s85, 0
	s_cmp_lg_u32 s2, 0
	s_cbranch_scc1 .Lgb23_wait
	s_mov_b64 s[8:9], exec
	s_mov_b64 exec, 1
	v_mov_b32_e32 v0, 0x12000
	ds_read_b64 v[2:3], v0
	v_mov_b32_e32 v0, 0x1400
	v_mov_b32_e32 v1, 1
	global_atomic_add v4, v0, v1, s[6:7] sc0
	s_mov_b32 s13, 0
	s_waitcnt lgkmcnt(0)
	v_readfirstlane_b32 s10, v2
	v_readfirstlane_b32 s11, v3
	v_mov_b32_e32 v0, 0x3400
	s_nop 3
	s_mul_i32 s10, s10, 19
	s_mul_i32 s11, s11, 19
	s_waitcnt vmcnt(0)
	v_readfirstlane_b32 s12, v4
	s_nop 3
	s_add_u32 s12, s12, 1
	s_cmp_lg_u32 s12, s10
	s_cbranch_scc1 .Lgb23_poll
	buffer_wbl2 sc1
	s_waitcnt vmcnt(0)
	global_atomic_add v4, v0, v1, s[84:85] sc0
	v_mov_b32_e32 v0, 0x3500
	s_waitcnt vmcnt(0)
	v_readfirstlane_b32 s12, v4
	s_nop 3
	s_add_u32 s12, s12, 1
	s_cmp_lg_u32 s12, s11
	s_cbranch_scc1 .Lgb23_poll
	global_atomic_add v0, v1, s[84:85]

.Lgb23_loop:
	global_load_dword v4, v0, s[84:85] sc1
	s_add_u32 s13, s13, 1
	s_waitcnt vmcnt(0)
	v_readfirstlane_b32 s12, v4
	s_nop 3
	s_cmp_gt_u32 s13, 0x80000
	s_cbranch_scc1 .Lgb23_done
	s_cmp_ge_u32 s12, 19
	s_cbranch_scc1 .Lgb23_done
	s_sleep 1
	s_branch .Lgb23_loop

.Lf24_end:
.LBB0_2420:
	s_cmp_lt_i32 s61, 25
	s_cbranch_scc1 .LBB0_2474
	s_waitcnt vmcnt(0) lgkmcnt(0)
	s_barrier
	v_readfirstlane_b32 s2, v162
	s_lshl_b32 s3, s33, 8
	s_add_u32 s6, s84, s3
	s_addc_u32 s7, s85, 0
	s_cmp_lg_u32 s2, 0
	s_cbranch_scc1 .Lgb24_wait
	s_mov_b64 s[8:9], exec
	s_mov_b64 exec, 1
	v_mov_b32_e32 v0, 0x12000
	ds_read_b64 v[2:3], v0
	v_mov_b32_e32 v0, 0x1400
	v_mov_b32_e32 v1, 1
	global_atomic_add v4, v0, v1, s[6:7] sc0
	s_mov_b32 s13, 0
	s_waitcnt lgkmcnt(0)
	v_readfirstlane_b32 s10, v2
	v_readfirstlane_b32 s11, v3
	v_mov_b32_e32 v0, 0x3400
	s_nop 3
	s_mul_i32 s10, s10, 20
	s_mul_i32 s11, s11, 20
	s_waitcnt vmcnt(0)
	v_readfirstlane_b32 s12, v4
	s_nop 3
	s_add_u32 s12, s12, 1
	s_cmp_lg_u32 s12, s10
	s_cbranch_scc1 .Lgb24_poll
	buffer_wbl2 sc1
	s_waitcnt vmcnt(0)
	global_atomic_add v4, v0, v1, s[84:85] sc0
	v_mov_b32_e32 v0, 0x3500
	s_waitcnt vmcnt(0)
	v_readfirstlane_b32 s12, v4
	s_nop 3
	s_add_u32 s12, s12, 1
	s_cmp_lg_u32 s12, s11
	s_cbranch_scc1 .Lgb24_poll
	global_atomic_add v0, v1, s[84:85]

.Lgb24_loop:
	global_load_dword v4, v0, s[84:85] sc1
	s_add_u32 s13, s13, 1
	s_waitcnt vmcnt(0)
	v_readfirstlane_b32 s12, v4
	s_nop 3
	s_cmp_gt_u32 s13, 0x80000
	s_cbranch_scc1 .Lgb24_done
	s_cmp_ge_u32 s12, 20
	s_cbranch_scc1 .Lgb24_done
	s_sleep 1
	s_branch .Lgb24_loop

.LBB0_2538:
	s_or_b64 exec, exec, s[10:11]
	s_cmp_lt_u32 s61, 27
	s_cbranch_scc1 .LBB0_2592
	s_waitcnt vmcnt(0) lgkmcnt(0)
	s_barrier
	v_readfirstlane_b32 s2, v162
	s_lshl_b32 s3, s33, 8
	s_add_u32 s6, s84, s3
	s_addc_u32 s7, s85, 0
	s_cmp_lg_u32 s2, 0
	s_cbranch_scc1 .Lgb26_wait
	s_mov_b64 s[8:9], exec
	s_mov_b64 exec, 1
	v_mov_b32_e32 v0, 0x12000
	ds_read_b64 v[2:3], v0
	v_mov_b32_e32 v0, 0x1400
	v_mov_b32_e32 v1, 1
	global_atomic_add v4, v0, v1, s[6:7] sc0
	s_mov_b32 s13, 0
	s_waitcnt lgkmcnt(0)
	v_readfirstlane_b32 s10, v2
	v_readfirstlane_b32 s11, v3
	v_mov_b32_e32 v0, 0x3400
	s_nop 3
	s_mul_i32 s10, s10, 21
	s_mul_i32 s11, s11, 21
	s_waitcnt vmcnt(0)
	v_readfirstlane_b32 s12, v4
	s_nop 3
	s_add_u32 s12, s12, 1
	s_cmp_lg_u32 s12, s10
	s_cbranch_scc1 .Lgb26_poll
	buffer_wbl2 sc1
	s_waitcnt vmcnt(0)
	global_atomic_add v4, v0, v1, s[84:85] sc0
	v_mov_b32_e32 v0, 0x3500
	s_waitcnt vmcnt(0)
	v_readfirstlane_b32 s12, v4
	s_nop 3
	s_add_u32 s12, s12, 1
	s_cmp_lg_u32 s12, s11
	s_cbranch_scc1 .Lgb26_poll
	global_atomic_add v0, v1, s[84:85]

.Lgb26_loop:
	global_load_dword v4, v0, s[84:85] sc1
	s_add_u32 s13, s13, 1
	s_waitcnt vmcnt(0)
	v_readfirstlane_b32 s12, v4
	s_nop 3
	s_cmp_gt_u32 s13, 0x80000
	s_cbranch_scc1 .Lgb26_done
	s_cmp_ge_u32 s12, 21
	s_cbranch_scc1 .Lgb26_done
	s_sleep 1
	s_branch .Lgb26_loop

.LBB0_2601:
	s_cmp_lt_i32 s61, 28
	s_cbranch_scc1 .LBB0_2655
	s_waitcnt vmcnt(0) lgkmcnt(0)
	s_barrier
	v_readfirstlane_b32 s2, v162
	s_lshl_b32 s3, s33, 8
	s_add_u32 s6, s84, s3
	s_addc_u32 s7, s85, 0
	s_cmp_lg_u32 s2, 0
	s_cbranch_scc1 .Lgb27_wait
	s_mov_b64 s[8:9], exec
	s_mov_b64 exec, 1
	v_mov_b32_e32 v0, 0x12000
	ds_read_b64 v[2:3], v0
	v_mov_b32_e32 v0, 0x1400
	v_mov_b32_e32 v1, 1
	global_atomic_add v4, v0, v1, s[6:7] sc0
	s_mov_b32 s13, 0
	s_waitcnt lgkmcnt(0)
	v_readfirstlane_b32 s10, v2
	v_readfirstlane_b32 s11, v3
	v_mov_b32_e32 v0, 0x3400
	s_nop 3
	s_mul_i32 s10, s10, 22
	s_mul_i32 s11, s11, 22
	s_waitcnt vmcnt(0)
	v_readfirstlane_b32 s12, v4
	s_nop 3
	s_add_u32 s12, s12, 1
	s_cmp_lg_u32 s12, s10
	s_cbranch_scc1 .Lgb27_poll
	buffer_wbl2 sc1
	s_waitcnt vmcnt(0)
	global_atomic_add v4, v0, v1, s[84:85] sc0
	v_mov_b32_e32 v0, 0x3500
	s_waitcnt vmcnt(0)
	v_readfirstlane_b32 s12, v4
	s_nop 3
	s_add_u32 s12, s12, 1
	s_cmp_lg_u32 s12, s11
	s_cbranch_scc1 .Lgb27_poll
	global_atomic_add v0, v1, s[84:85]

.Lgb27_loop:
	global_load_dword v4, v0, s[84:85] sc1
	s_add_u32 s13, s13, 1
	s_waitcnt vmcnt(0)
	v_readfirstlane_b32 s12, v4
	s_nop 3
	s_cmp_gt_u32 s13, 0x80000
	s_cbranch_scc1 .Lgb27_done
	s_cmp_ge_u32 s12, 22
	s_cbranch_scc1 .Lgb27_done
	s_sleep 1
	s_branch .Lgb27_loop

.LBB0_2665:
	s_cmp_lt_i32 s61, 29
	s_cbranch_scc1 .LBB0_2719
	s_waitcnt vmcnt(0) lgkmcnt(0)
	s_barrier
	v_readfirstlane_b32 s2, v162
	s_lshl_b32 s3, s33, 8
	s_add_u32 s6, s84, s3
	s_addc_u32 s7, s85, 0
	s_cmp_lg_u32 s2, 0
	s_cbranch_scc1 .Lgb28_wait
	s_mov_b64 s[8:9], exec
	s_mov_b64 exec, 1
	v_mov_b32_e32 v0, 0x12000
	ds_read_b64 v[2:3], v0
	v_mov_b32_e32 v0, 0x1400
	v_mov_b32_e32 v1, 1
	global_atomic_add v4, v0, v1, s[6:7] sc0
	s_mov_b32 s13, 0
	s_waitcnt lgkmcnt(0)
	v_readfirstlane_b32 s10, v2
	v_readfirstlane_b32 s11, v3
	v_mov_b32_e32 v0, 0x3400
	s_nop 3
	s_mul_i32 s10, s10, 23
	s_mul_i32 s11, s11, 23
	s_waitcnt vmcnt(0)
	v_readfirstlane_b32 s12, v4
	s_nop 3
	s_add_u32 s12, s12, 1
	s_cmp_lg_u32 s12, s10
	s_cbranch_scc1 .Lgb28_poll
	buffer_wbl2 sc1
	s_waitcnt vmcnt(0)
	global_atomic_add v4, v0, v1, s[84:85] sc0
	v_mov_b32_e32 v0, 0x3500
	s_waitcnt vmcnt(0)
	v_readfirstlane_b32 s12, v4
	s_nop 3
	s_add_u32 s12, s12, 1
	s_cmp_lg_u32 s12, s11
	s_cbranch_scc1 .Lgb28_poll
	global_atomic_add v0, v1, s[84:85]

.Lgb28_loop:
	global_load_dword v4, v0, s[84:85] sc1
	s_add_u32 s13, s13, 1
	s_waitcnt vmcnt(0)
	v_readfirstlane_b32 s12, v4
	s_nop 3
	s_cmp_gt_u32 s13, 0x80000
	s_cbranch_scc1 .Lgb28_done
	s_cmp_ge_u32 s12, 23
	s_cbranch_scc1 .Lgb28_done
	s_sleep 1
	s_branch .Lgb28_loop

.LBB0_2791:
	s_or_b64 exec, exec, s[10:11]
	s_cmp_lt_u32 s61, 31
	s_cbranch_scc1 .LBB0_2845
	s_waitcnt vmcnt(0) lgkmcnt(0)
	s_barrier
	v_readfirstlane_b32 s2, v162
	s_lshl_b32 s3, s33, 8
	s_add_u32 s6, s84, s3
	s_addc_u32 s7, s85, 0
	s_cmp_lg_u32 s2, 0
	s_cbranch_scc1 .Lgb30_wait
	s_mov_b64 s[8:9], exec
	s_mov_b64 exec, 1
	v_mov_b32_e32 v0, 0x12000
	ds_read_b64 v[2:3], v0
	v_mov_b32_e32 v0, 0x1400
	v_mov_b32_e32 v1, 1
	global_atomic_add v4, v0, v1, s[6:7] sc0
	s_mov_b32 s13, 0
	s_waitcnt lgkmcnt(0)
	v_readfirstlane_b32 s10, v2
	v_readfirstlane_b32 s11, v3
	v_mov_b32_e32 v0, 0x3400
	s_nop 3
	s_mul_i32 s10, s10, 24
	s_mul_i32 s11, s11, 24
	s_waitcnt vmcnt(0)
	v_readfirstlane_b32 s12, v4
	s_nop 3
	s_add_u32 s12, s12, 1
	s_cmp_lg_u32 s12, s10
	s_cbranch_scc1 .Lgb30_poll
	buffer_wbl2 sc1
	s_waitcnt vmcnt(0)
	global_atomic_add v4, v0, v1, s[84:85] sc0
	v_mov_b32_e32 v0, 0x3500
	s_waitcnt vmcnt(0)
	v_readfirstlane_b32 s12, v4
	s_nop 3
	s_add_u32 s12, s12, 1
	s_cmp_lg_u32 s12, s11
	s_cbranch_scc1 .Lgb30_poll
	global_atomic_add v0, v1, s[84:85]

.Lgb30_loop:
	global_load_dword v4, v0, s[84:85] sc1
	s_add_u32 s13, s13, 1
	s_waitcnt vmcnt(0)
	v_readfirstlane_b32 s12, v4
	s_nop 3
	s_cmp_gt_u32 s13, 0x80000
	s_cbranch_scc1 .Lgb30_done
	s_cmp_ge_u32 s12, 24
	s_cbranch_scc1 .Lgb30_done
	s_sleep 1
	s_branch .Lgb30_loop

.Lf31_end:
.LBB0_2855:
	s_cmp_lt_i32 s61, 32
	s_cbranch_scc1 .LBB0_2909
	s_waitcnt vmcnt(0) lgkmcnt(0)
	s_barrier
	v_readfirstlane_b32 s2, v162
	s_lshl_b32 s3, s33, 8
	s_add_u32 s6, s84, s3
	s_addc_u32 s7, s85, 0
	s_cmp_lg_u32 s2, 0
	s_cbranch_scc1 .Lgb31_wait
	s_mov_b64 s[8:9], exec
	s_mov_b64 exec, 1
	v_mov_b32_e32 v0, 0x12000
	ds_read_b64 v[2:3], v0
	v_mov_b32_e32 v0, 0x1400
	v_mov_b32_e32 v1, 1
	global_atomic_add v4, v0, v1, s[6:7] sc0
	s_mov_b32 s13, 0
	s_waitcnt lgkmcnt(0)
	v_readfirstlane_b32 s10, v2
	v_readfirstlane_b32 s11, v3
	v_mov_b32_e32 v0, 0x3400
	s_nop 3
	s_mul_i32 s10, s10, 25
	s_mul_i32 s11, s11, 25
	s_waitcnt vmcnt(0)
	v_readfirstlane_b32 s12, v4
	s_nop 3
	s_add_u32 s12, s12, 1
	s_cmp_lg_u32 s12, s10
	s_cbranch_scc1 .Lgb31_poll
	buffer_wbl2 sc1
	s_waitcnt vmcnt(0)
	global_atomic_add v4, v0, v1, s[84:85] sc0
	v_mov_b32_e32 v0, 0x3500
	s_waitcnt vmcnt(0)
	v_readfirstlane_b32 s12, v4
	s_nop 3
	s_add_u32 s12, s12, 1
	s_cmp_lg_u32 s12, s11
	s_cbranch_scc1 .Lgb31_poll
	global_atomic_add v0, v1, s[84:85]

.Lgb31_loop:
	global_load_dword v4, v0, s[84:85] sc1
	s_add_u32 s13, s13, 1
	s_waitcnt vmcnt(0)
	v_readfirstlane_b32 s12, v4
	s_nop 3
	s_cmp_gt_u32 s13, 0x80000
	s_cbranch_scc1 .Lgb31_done
	s_cmp_ge_u32 s12, 25
	s_cbranch_scc1 .Lgb31_done
	s_sleep 1
	s_branch .Lgb31_loop
